# added: GLA-prep gate loop - 16 ds_read_b128 per 2-row body hoisted into distinct registers with one wait (was 16 serialized waits)
# speedup vs baseline: 1.0355x; 1.0103x over previous
; LPHASE void phase_gla_prep(char* ws_, const float* x_, float* out_, const float* meta_, int nseq_, char* lds) {
;     ...
; #pragma unroll 2
;       for (int ii = 0; ii < 16; ++ii) { const int i = ig * 16 + ii; float sf = bfv, sb = bbv; const float* a = af + i * 32;
; #pragma unroll
;         for (int k = 0; k < 16; ++k) { sf += a[k] * wf[k]; sb += a[16 + k] * wb[k]; }
;         float lf = (fminf(sf, 0.f) - __logf(1.f + __expf(-fabsf(sf)))) * (1.f / 16.f), lb = (fminf(sb, 0.f) - __logf(1.f + __expf(-fabsf(sb)))) * (1.f / 16.f);
;         if (ismeta && i >= 16) { lf = 0.f; lb = 0.f; }
;         lgF[i * LGP + d] = lf; lgB[i * LGP + d] = lb; tfl += lf; tbl += lb; }
.LBB0_506:
	v_add_u32_e32 v85, s12, v80
	v_add_u32_e32 v96, 0x10200, v85
	ds_read_b128 v[100:103], v96
	ds_read_b128 v[104:107], v96 offset:64
	ds_read_b128 v[108:111], v96 offset:16
	ds_read_b128 v[112:115], v96 offset:80
	ds_read_b128 v[116:119], v96 offset:32
	ds_read_b128 v[120:123], v96 offset:96
	ds_read_b128 v[124:127], v96 offset:48
	ds_read_b128 v[128:131], v96 offset:112
	ds_read_b128 v[136:139], v96 offset:128
	ds_read_b128 v[140:143], v96 offset:192
	ds_read_b128 v[144:147], v96 offset:144
	ds_read_b128 v[148:151], v96 offset:208
	ds_read_b128 v[152:155], v96 offset:160
	ds_read_b128 v[156:159], v96 offset:224
	ds_read_b128 v[160:163], v96 offset:176
	ds_read_b128 v[164:167], v96 offset:240
	s_waitcnt vmcnt(0) lgkmcnt(0)
	s_addk_i32 s12, 0x100
	v_fma_f32 v94, v74, v100, v78
	v_fmac_f32_e32 v94, v77, v101
	v_fmac_f32_e32 v94, v62, v102
	v_fmac_f32_e32 v94, v70, v103
	v_fma_f32 v95, v75, v104, v79
	v_fmac_f32_e32 v95, v76, v105
	v_fmac_f32_e32 v95, v63, v106
	v_fmac_f32_e32 v95, v71, v107
	v_fmac_f32_e32 v94, v64, v108
	v_fmac_f32_e32 v94, v68, v109
	v_fmac_f32_e32 v94, v67, v110
	v_fmac_f32_e32 v94, v72, v111
	v_fmac_f32_e32 v95, v65, v112
	v_fmac_f32_e32 v95, v66, v113
	v_fmac_f32_e32 v95, v69, v114
	v_fmac_f32_e32 v95, v73, v115
	v_pk_mul_f32 v[86:87], v[4:5], v[116:117]
	s_nop 0
	v_add_f32_e32 v86, v94, v86
	v_add_f32_e32 v94, v86, v87
	v_pk_mul_f32 v[86:87], v[6:7], v[120:121]
	s_nop 0
	v_add_f32_e32 v86, v95, v86
	v_add_f32_e32 v90, v86, v87
	v_pk_mul_f32 v[86:87], v[8:9], v[118:119]
	s_nop 0
	v_add_f32_e32 v86, v94, v86
	v_add_f32_e32 v91, v86, v87
	v_pk_mul_f32 v[86:87], v[10:11], v[122:123]
	s_nop 0
	v_add_f32_e32 v86, v90, v86
	v_add_f32_e32 v94, v86, v87
	v_pk_mul_f32 v[86:87], v[12:13], v[124:125]
	s_nop 0
	v_add_f32_e32 v86, v91, v86
	v_add_f32_e32 v95, v86, v87
	v_pk_mul_f32 v[86:87], v[14:15], v[128:129]
	s_nop 0
	v_add_f32_e32 v86, v94, v86
	v_add_f32_e32 v90, v86, v87
	v_pk_mul_f32 v[86:87], v[22:23], v[126:127]
	s_nop 0
	v_add_f32_e32 v86, v95, v86
	v_add_f32_e32 v88, v86, v87
	v_pk_mul_f32 v[86:87], v[24:25], v[130:131]
	s_nop 0
	v_add_f32_e32 v86, v90, v86
	v_add_f32_e32 v86, v86, v87
	v_min_f32_e32 v87, 0, v88
	v_mul_f32_e64 v88, |v88|, s6
	v_exp_f32_e32 v88, v88
	s_nop 0
	v_add_f32_e32 v88, 1.0, v88
	v_cmp_gt_f32_e32 vcc, s93, v88
	s_nop 1
	v_cndmask_b32_e64 v89, 0, 32, vcc
	v_ldexp_f32 v88, v88, v89
	v_log_f32_e32 v88, v88
	s_nop 0
	v_mul_f32_e32 v89, 0x3f317217, v88
	v_fma_f32 v89, v88, s13, -v89
	v_fmac_f32_e32 v89, 0x3377d1cf, v88
	v_fmac_f32_e32 v89, 0x3f317217, v88
	v_cmp_lt_f32_e64 s[0:1], |v88|, s14
	s_nop 1
	v_cndmask_b32_e64 v88, v88, v89, s[0:1]
	v_cndmask_b32_e32 v89, 0, v243, vcc
	v_sub_f32_e32 v88, v88, v89
	v_sub_f32_e32 v87, v87, v88
	v_min_f32_e32 v88, 0, v86
	v_mul_f32_e64 v86, |v86|, s6
	v_exp_f32_e32 v86, v86
	v_mul_f32_e32 v87, 0x3d800000, v87
	v_add_f32_e32 v86, 1.0, v86
	v_cmp_gt_f32_e32 vcc, s93, v86
	s_nop 1
	v_cndmask_b32_e64 v89, 0, 32, vcc
	v_ldexp_f32 v86, v86, v89
	v_log_f32_e32 v86, v86
	s_nop 0
	v_mul_f32_e32 v89, 0x3f317217, v86
	v_fma_f32 v89, v86, s13, -v89
	v_fmac_f32_e32 v89, 0x3377d1cf, v86
	v_fmac_f32_e32 v89, 0x3f317217, v86
	v_cmp_lt_f32_e64 s[0:1], |v86|, s14
	s_nop 1
	v_cndmask_b32_e64 v86, v86, v89, s[0:1]
	v_cndmask_b32_e32 v89, 0, v243, vcc
	v_sub_f32_e32 v86, v86, v89
	v_sub_f32_e32 v86, v88, v86
	v_cmp_lt_i32_e32 vcc, 15, v82
	v_mul_f32_e32 v86, 0x3d800000, v86
	s_and_b64 s[0:1], s[26:27], vcc
	v_cndmask_b32_e64 v86, v86, 0, s[0:1]
	v_cndmask_b32_e64 v87, v87, 0, s[0:1]
	ds_write_b32 v81, v87
	ds_write_b32 v81, v86 offset:33024
	v_add_f32_e32 v84, v84, v86
	v_add_f32_e32 v83, v83, v87
	v_fma_f32 v94, v74, v136, v78
	v_fmac_f32_e32 v94, v77, v137
	v_fmac_f32_e32 v94, v62, v138
	v_fmac_f32_e32 v94, v70, v139
	v_fma_f32 v95, v75, v140, v79
	v_fmac_f32_e32 v95, v76, v141
	v_fmac_f32_e32 v95, v63, v142
	v_fmac_f32_e32 v95, v71, v143
	v_fmac_f32_e32 v94, v64, v144
	v_fmac_f32_e32 v94, v68, v145
	v_fmac_f32_e32 v94, v67, v146
	v_fmac_f32_e32 v94, v72, v147
	v_fmac_f32_e32 v95, v65, v148
	v_fmac_f32_e32 v95, v66, v149
	v_fmac_f32_e32 v95, v69, v150
	v_fmac_f32_e32 v95, v73, v151
	v_pk_mul_f32 v[86:87], v[4:5], v[152:153]
	s_nop 0
	v_add_f32_e32 v86, v94, v86
	v_add_f32_e32 v94, v86, v87
	v_pk_mul_f32 v[86:87], v[6:7], v[156:157]
	s_nop 0
	v_add_f32_e32 v86, v95, v86
	v_add_f32_e32 v90, v86, v87
	v_pk_mul_f32 v[86:87], v[8:9], v[154:155]
	s_nop 0
	v_add_f32_e32 v86, v94, v86
	v_add_f32_e32 v91, v86, v87
	v_pk_mul_f32 v[86:87], v[10:11], v[158:159]
	s_nop 0
	v_add_f32_e32 v86, v90, v86
	v_add_f32_e32 v94, v86, v87
	v_pk_mul_f32 v[86:87], v[12:13], v[160:161]
	s_nop 0
	v_add_f32_e32 v86, v91, v86
	v_add_f32_e32 v95, v86, v87
	v_pk_mul_f32 v[86:87], v[14:15], v[164:165]
	s_nop 0
	v_add_f32_e32 v85, v94, v86
	v_add_f32_e32 v85, v85, v87
	v_pk_mul_f32 v[86:87], v[22:23], v[162:163]
	s_nop 0
	v_add_f32_e32 v86, v95, v86
	v_add_f32_e32 v88, v86, v87
	v_pk_mul_f32 v[86:87], v[24:25], v[166:167]
	s_nop 0
	v_add_f32_e32 v85, v85, v86
	v_add_f32_e32 v85, v85, v87
	v_mul_f32_e64 v87, |v88|, s6
	v_exp_f32_e32 v87, v87
	v_min_f32_e32 v86, 0, v88
	v_add_f32_e32 v87, 1.0, v87
	v_cmp_gt_f32_e32 vcc, s93, v87
	s_nop 1
	v_cndmask_b32_e64 v88, 0, 32, vcc
	v_ldexp_f32 v87, v87, v88
	v_log_f32_e32 v87, v87
	s_nop 0
	v_mul_f32_e32 v88, 0x3f317217, v87
	v_fma_f32 v88, v87, s13, -v88
	v_fmac_f32_e32 v88, 0x3377d1cf, v87
	v_fmac_f32_e32 v88, 0x3f317217, v87
	v_cmp_lt_f32_e64 s[0:1], |v87|, s14
	s_nop 1
	v_cndmask_b32_e64 v87, v87, v88, s[0:1]
	v_cndmask_b32_e32 v88, 0, v243, vcc
	v_sub_f32_e32 v87, v87, v88
	v_sub_f32_e32 v86, v86, v87
	v_min_f32_e32 v87, 0, v85
	v_mul_f32_e64 v85, |v85|, s6
	v_exp_f32_e32 v85, v85
	v_mul_f32_e32 v86, 0x3d800000, v86
	v_add_f32_e32 v85, 1.0, v85
	v_cmp_gt_f32_e32 vcc, s93, v85
	s_nop 1
	v_cndmask_b32_e64 v88, 0, 32, vcc
	v_ldexp_f32 v85, v85, v88
	v_log_f32_e32 v85, v85
	s_nop 0
	v_mul_f32_e32 v88, 0x3f317217, v85
	v_fma_f32 v88, v85, s13, -v88
	v_fmac_f32_e32 v88, 0x3377d1cf, v85
	v_fmac_f32_e32 v88, 0x3f317217, v85
	v_cmp_lt_f32_e64 s[0:1], |v85|, s14
	s_nop 1
	v_cndmask_b32_e64 v85, v85, v88, s[0:1]
	v_cndmask_b32_e32 v88, 0, v243, vcc
	v_sub_f32_e32 v85, v85, v88
	v_sub_f32_e32 v85, v87, v85
	v_cmp_lt_i32_e32 vcc, 14, v82
	v_mul_f32_e32 v85, 0x3d800000, v85
	s_and_b64 s[0:1], s[26:27], vcc
	v_cndmask_b32_e64 v85, v85, 0, s[0:1]
	v_cndmask_b32_e64 v86, v86, 0, s[0:1]
	ds_write_b32 v81, v86 offset:516
	ds_write_b32 v81, v85 offset:33540
	v_add_f32_e32 v83, v83, v86
	v_add_f32_e32 v84, v84, v85
	v_add_u32_e32 v82, 2, v82
	v_add_u32_e32 v81, 0x408, v81
	s_cmpk_eq_i32 s12, 0x800
	s_cbranch_scc0 .LBB0_506
; LPHASE void phase_gla_prep(char* ws_, const float* x_, float* out_, const float* meta_, int nseq_, char* lds) {
;     ...
;       tot[ig * 128 + d] = tfl; tot[512 + ig * 128 + d] = tbl;
;     }
;     __syncthreads();
;     { const float t0 = tot[d], t1 = tot[128 + d], t2 = tot[256 + d], t3 = tot[384 + d];
;       const float u0 = tot[512 + d], u1 = tot[640 + d], u2 = tot[768 + d], u3 = tot[896 + d];
;       const float blF = (t0 + t1) + (t2 + t3), brF = t0 + t1, blB = (u0 + u1) + (u2 + u3), brB = u2 + u3;
;       const float offF = ig == 0 ? 0.f : ig == 1 ? t0 : ig == 2 ? t0 + t1 : (t0 + t1) + t2;
;       const float offB = ig == 3 ? 0.f : ig == 2 ? u3 : ig == 1 ? u2 + u3 : (u1 + u2) + u3;
;       const float myB = ig == 0 ? u0 : ig == 1 ? u1 : ig == 2 ? u2 : u3;
	v_and_b32_e32 v4, 0x3fffff80, v16
	v_lshl_add_u32 v6, v2, 2, s85
	v_lshl_add_u32 v5, v16, 2, s85
	v_lshl_add_u32 v4, v4, 2, v6
	ds_write_b32 v5, v83
	ds_write_b32 v4, v84 offset:2048
	s_waitcnt lgkmcnt(0)
	s_barrier
	ds_read2st64_b32 v[10:11], v6 offset1:2
	ds_read2st64_b32 v[8:9], v6 offset0:4 offset1:6
	ds_read2st64_b32 v[4:5], v6 offset0:8 offset1:10
	ds_read2st64_b32 v[6:7], v6 offset0:12 offset1:14
	s_movk_i32 s0, 0x80
	v_cmp_gt_u32_e32 vcc, s0, v16
	s_movk_i32 s0, 0x7f
	s_waitcnt lgkmcnt(3)
	v_add_f32_e32 v11, v10, v11
	v_cmp_lt_u32_e64 s[0:1], s0, v16
	v_mov_b32_e32 v13, 0
	s_and_saveexec_b64 s[26:27], s[0:1]
	s_cbranch_execz .LBB0_513
	v_cmp_lt_i32_e64 s[0:1], 1, v49
	s_mov_b64 s[28:29], 0
	s_and_saveexec_b64 s[30:31], s[0:1]
	s_xor_b64 s[42:43], exec, s[30:31]
	s_cbranch_execnz .LBB0_527
	s_or_saveexec_b64 s[42:43], s[42:43]
	v_mov_b32_e32 v13, v11
	s_xor_b64 exec, exec, s[42:43]
	s_cbranch_execnz .LBB0_530
